# placement test: +128 B shift of code after the 2b remap
# speedup vs baseline: 1.0098x; 1.0032x over previous
; __global__ void __launch_bounds__(256, 2) mega(Params p) {
;     ...
;     for (int rep = 0; rep < REP_2B; ++rep) {
;       bool first = true;
;       for (;;) {
;         int it;
;         if (first) { it = (int)blockIdx.x; first = false; }
;         else it = next_item(ctr + layer * 2 + 1 + 8 * rep, &slot) + (int)gridDim.x;
;         if (rep > 0) { it += PROBE_2B_LO; if (it >= PROBE_2B_HI) break; }
;         if (it >= 288 + 192 + 24 + 256 + 1536) break;
;         it = (it < 192) ? (it + 384) : ((it < 480) ? (it - 192) : ((it < 504) ? (it + 608) : ((it < 760) ? (it + 328) : (it + 352))));
.LBB0_354:
	s_or_b64 exec, exec, s[0:1]
	s_mul_i32 s0, s69, 12
	v_writelane_b32 v255, s0, 51
	v_readlane_b32 s2, v252, 0
	s_waitcnt lgkmcnt(0)
	s_barrier
	s_nop 0
	s_nop 0
	s_nop 0
	s_nop 0
	s_nop 0
	s_nop 0
	s_nop 0
	s_nop 0
	s_nop 0
	s_nop 0
	s_nop 0
	s_nop 0
	s_nop 0
	s_nop 0
	s_nop 0
	s_nop 0
	s_nop 0
	s_nop 0
	s_nop 0
	s_nop 0
	s_nop 0
	s_nop 0
	s_nop 0
	s_nop 0
	s_nop 0
	s_nop 0
	s_nop 0
	v_readlane_b32 s98, v255, 38
	s_cmp_eq_u32 s98, 0x200
	s_cbranch_scc0 .Lmap2b_done
	s_cmp_lt_u32 s2, 192
	s_cbranch_scc1 .Lmap2b_done
	s_cmp_lt_u32 s2, 224
	s_cbranch_scc0 .Lmap2b_a
	s_add_i32 s2, s2, 128
	s_branch .Lmap2b_done
